# P1 q/k epilogue hand-written: rstd and gains loaded once, batched cross-lane reductions, stores never waited
# speedup vs baseline: 1.1105x; 1.0058x over previous
.LBB0_143:
	v_ashrrev_i32_e32 v141, 31, v140
	s_cmp_lt_i32 s94, 2
	s_cselect_b64 vcc, -1, 0
	s_and_b64 s[38:39], vcc, exec
	s_cselect_b32 s55, s57, s59
	s_cselect_b32 s54, s56, s58
	s_cselect_b32 s12, s47, s79
	s_cselect_b32 s35, s46, s78
	s_lshl_b32 s37, s94, 9
	s_and_b32 s37, s37, 0x200
	s_add_u32 s64, s35, s37
	s_addc_u32 s65, s12, 0
	v_lshlrev_b32_e32 v236, 2, v140
	global_load_dword v202, v236, s[18:19]
	global_load_dword v204, v236, s[18:19] offset:64
	global_load_dword v206, v236, s[18:19] offset:128
	global_load_dword v208, v236, s[18:19] offset:192
	global_load_dword v210, v236, s[18:19] offset:512
	global_load_dword v212, v236, s[18:19] offset:576
	global_load_dword v214, v236, s[18:19] offset:640
	global_load_dword v216, v236, s[18:19] offset:704
	global_load_dwordx4 v[186:189], v180, s[54:55]
	global_load_dwordx4 v[190:193], v180, s[54:55] offset:16
	global_load_dwordx4 v[194:197], v180, s[54:55] offset:32
	global_load_dwordx4 v[198:201], v180, s[54:55] offset:48
	v_cndmask_b32_e32 v144, 1.0, v183, vcc
	v_xor_b32_e32 v234, 16, v184
	v_xor_b32_e32 v235, 32, v184
	v_lshlrev_b32_e32 v234, 2, v234
	v_lshlrev_b32_e32 v235, 2, v235
	v_lshlrev_b64 v[238:239], 10, v[140:141]
	v_lshlrev_b32_e32 v130, 1, v128
	v_lshl_add_u64 v[238:239], s[64:65], 0, v[238:239]
	v_lshl_add_u64 v[238:239], v[238:239], 0, v[130:131]
	s_waitcnt vmcnt(4)
	v_pk_mul_f32 v[124:125], v[124:125], v[202:203] op_sel_hi:[1,0]
	v_pk_mul_f32 v[126:127], v[126:127], v[202:203] op_sel_hi:[1,0]
	v_pk_mul_f32 v[120:121], v[120:121], v[202:203] op_sel_hi:[1,0]
	v_pk_mul_f32 v[122:123], v[122:123], v[202:203] op_sel_hi:[1,0]
	v_pk_mul_f32 v[116:117], v[116:117], v[202:203] op_sel_hi:[1,0]
	v_pk_mul_f32 v[118:119], v[118:119], v[202:203] op_sel_hi:[1,0]
	v_pk_mul_f32 v[112:113], v[112:113], v[202:203] op_sel_hi:[1,0]
	v_pk_mul_f32 v[114:115], v[114:115], v[202:203] op_sel_hi:[1,0]
	v_pk_mul_f32 v[146:147], v[124:125], v[124:125]
	v_pk_mul_f32 v[148:149], v[126:127], v[126:127]
	v_pk_fma_f32 v[146:147], v[120:121], v[120:121], v[146:147]
	v_pk_fma_f32 v[148:149], v[122:123], v[122:123], v[148:149]
	v_pk_fma_f32 v[146:147], v[116:117], v[116:117], v[146:147]
	v_pk_fma_f32 v[148:149], v[118:119], v[118:119], v[148:149]
	v_pk_fma_f32 v[146:147], v[112:113], v[112:113], v[146:147]
	v_pk_fma_f32 v[148:149], v[114:115], v[114:115], v[148:149]
	s_nop 0
	v_pk_add_f32 v[146:147], v[146:147], v[148:149]
	s_nop 0
	v_add_f32_e32 v218, v146, v147
	v_pk_mul_f32 v[108:109], v[108:109], v[204:205] op_sel_hi:[1,0]
	v_pk_mul_f32 v[110:111], v[110:111], v[204:205] op_sel_hi:[1,0]
	v_pk_mul_f32 v[104:105], v[104:105], v[204:205] op_sel_hi:[1,0]
	v_pk_mul_f32 v[106:107], v[106:107], v[204:205] op_sel_hi:[1,0]
	v_pk_mul_f32 v[100:101], v[100:101], v[204:205] op_sel_hi:[1,0]
	v_pk_mul_f32 v[102:103], v[102:103], v[204:205] op_sel_hi:[1,0]
	v_pk_mul_f32 v[96:97], v[96:97], v[204:205] op_sel_hi:[1,0]
	v_pk_mul_f32 v[98:99], v[98:99], v[204:205] op_sel_hi:[1,0]
	v_pk_mul_f32 v[146:147], v[108:109], v[108:109]
	v_pk_mul_f32 v[148:149], v[110:111], v[110:111]
	v_pk_fma_f32 v[146:147], v[104:105], v[104:105], v[146:147]
	v_pk_fma_f32 v[148:149], v[106:107], v[106:107], v[148:149]
	v_pk_fma_f32 v[146:147], v[100:101], v[100:101], v[146:147]
	v_pk_fma_f32 v[148:149], v[102:103], v[102:103], v[148:149]
	v_pk_fma_f32 v[146:147], v[96:97], v[96:97], v[146:147]
	v_pk_fma_f32 v[148:149], v[98:99], v[98:99], v[148:149]
	s_nop 0
	v_pk_add_f32 v[146:147], v[146:147], v[148:149]
	s_nop 0
	v_add_f32_e32 v219, v146, v147
	v_pk_mul_f32 v[92:93], v[92:93], v[206:207] op_sel_hi:[1,0]
	v_pk_mul_f32 v[94:95], v[94:95], v[206:207] op_sel_hi:[1,0]
	v_pk_mul_f32 v[88:89], v[88:89], v[206:207] op_sel_hi:[1,0]
	v_pk_mul_f32 v[90:91], v[90:91], v[206:207] op_sel_hi:[1,0]
	v_pk_mul_f32 v[84:85], v[84:85], v[206:207] op_sel_hi:[1,0]
	v_pk_mul_f32 v[86:87], v[86:87], v[206:207] op_sel_hi:[1,0]
	v_pk_mul_f32 v[80:81], v[80:81], v[206:207] op_sel_hi:[1,0]
	v_pk_mul_f32 v[82:83], v[82:83], v[206:207] op_sel_hi:[1,0]
	v_pk_mul_f32 v[146:147], v[92:93], v[92:93]
	v_pk_mul_f32 v[148:149], v[94:95], v[94:95]
	v_pk_fma_f32 v[146:147], v[88:89], v[88:89], v[146:147]
	v_pk_fma_f32 v[148:149], v[90:91], v[90:91], v[148:149]
	v_pk_fma_f32 v[146:147], v[84:85], v[84:85], v[146:147]
	v_pk_fma_f32 v[148:149], v[86:87], v[86:87], v[148:149]
	v_pk_fma_f32 v[146:147], v[80:81], v[80:81], v[146:147]
	v_pk_fma_f32 v[148:149], v[82:83], v[82:83], v[148:149]
	s_nop 0
	v_pk_add_f32 v[146:147], v[146:147], v[148:149]
	s_nop 0
	v_add_f32_e32 v220, v146, v147
	v_pk_mul_f32 v[76:77], v[76:77], v[208:209] op_sel_hi:[1,0]
	v_pk_mul_f32 v[78:79], v[78:79], v[208:209] op_sel_hi:[1,0]
	v_pk_mul_f32 v[72:73], v[72:73], v[208:209] op_sel_hi:[1,0]
	v_pk_mul_f32 v[74:75], v[74:75], v[208:209] op_sel_hi:[1,0]
	v_pk_mul_f32 v[68:69], v[68:69], v[208:209] op_sel_hi:[1,0]
	v_pk_mul_f32 v[70:71], v[70:71], v[208:209] op_sel_hi:[1,0]
	v_pk_mul_f32 v[64:65], v[64:65], v[208:209] op_sel_hi:[1,0]
	v_pk_mul_f32 v[66:67], v[66:67], v[208:209] op_sel_hi:[1,0]
	v_pk_mul_f32 v[146:147], v[76:77], v[76:77]
	v_pk_mul_f32 v[148:149], v[78:79], v[78:79]
	v_pk_fma_f32 v[146:147], v[72:73], v[72:73], v[146:147]
	v_pk_fma_f32 v[148:149], v[74:75], v[74:75], v[148:149]
	v_pk_fma_f32 v[146:147], v[68:69], v[68:69], v[146:147]
	v_pk_fma_f32 v[148:149], v[70:71], v[70:71], v[148:149]
	v_pk_fma_f32 v[146:147], v[64:65], v[64:65], v[146:147]
	v_pk_fma_f32 v[148:149], v[66:67], v[66:67], v[148:149]
	s_nop 0
	v_pk_add_f32 v[146:147], v[146:147], v[148:149]
	s_nop 0
	v_add_f32_e32 v221, v146, v147
	v_pk_mul_f32 v[60:61], v[60:61], v[210:211] op_sel_hi:[1,0]
	v_pk_mul_f32 v[62:63], v[62:63], v[210:211] op_sel_hi:[1,0]
	v_pk_mul_f32 v[56:57], v[56:57], v[210:211] op_sel_hi:[1,0]
	v_pk_mul_f32 v[58:59], v[58:59], v[210:211] op_sel_hi:[1,0]
	v_pk_mul_f32 v[52:53], v[52:53], v[210:211] op_sel_hi:[1,0]
	v_pk_mul_f32 v[54:55], v[54:55], v[210:211] op_sel_hi:[1,0]
	v_pk_mul_f32 v[48:49], v[48:49], v[210:211] op_sel_hi:[1,0]
	v_pk_mul_f32 v[50:51], v[50:51], v[210:211] op_sel_hi:[1,0]
	v_pk_mul_f32 v[146:147], v[60:61], v[60:61]
	v_pk_mul_f32 v[148:149], v[62:63], v[62:63]
	v_pk_fma_f32 v[146:147], v[56:57], v[56:57], v[146:147]
	v_pk_fma_f32 v[148:149], v[58:59], v[58:59], v[148:149]
	v_pk_fma_f32 v[146:147], v[52:53], v[52:53], v[146:147]
	v_pk_fma_f32 v[148:149], v[54:55], v[54:55], v[148:149]
	v_pk_fma_f32 v[146:147], v[48:49], v[48:49], v[146:147]
	v_pk_fma_f32 v[148:149], v[50:51], v[50:51], v[148:149]
	s_nop 0
	v_pk_add_f32 v[146:147], v[146:147], v[148:149]
	s_nop 0
	v_add_f32_e32 v222, v146, v147
	v_pk_mul_f32 v[44:45], v[44:45], v[212:213] op_sel_hi:[1,0]
	v_pk_mul_f32 v[46:47], v[46:47], v[212:213] op_sel_hi:[1,0]
	v_pk_mul_f32 v[40:41], v[40:41], v[212:213] op_sel_hi:[1,0]
	v_pk_mul_f32 v[42:43], v[42:43], v[212:213] op_sel_hi:[1,0]
	v_pk_mul_f32 v[36:37], v[36:37], v[212:213] op_sel_hi:[1,0]
	v_pk_mul_f32 v[38:39], v[38:39], v[212:213] op_sel_hi:[1,0]
	v_pk_mul_f32 v[32:33], v[32:33], v[212:213] op_sel_hi:[1,0]
	v_pk_mul_f32 v[34:35], v[34:35], v[212:213] op_sel_hi:[1,0]
	v_pk_mul_f32 v[146:147], v[44:45], v[44:45]
	v_pk_mul_f32 v[148:149], v[46:47], v[46:47]
	v_pk_fma_f32 v[146:147], v[40:41], v[40:41], v[146:147]
	v_pk_fma_f32 v[148:149], v[42:43], v[42:43], v[148:149]
	v_pk_fma_f32 v[146:147], v[36:37], v[36:37], v[146:147]
	v_pk_fma_f32 v[148:149], v[38:39], v[38:39], v[148:149]
	v_pk_fma_f32 v[146:147], v[32:33], v[32:33], v[146:147]
	v_pk_fma_f32 v[148:149], v[34:35], v[34:35], v[148:149]
	s_nop 0
	v_pk_add_f32 v[146:147], v[146:147], v[148:149]
	s_nop 0
	v_add_f32_e32 v223, v146, v147
	v_pk_mul_f32 v[28:29], v[28:29], v[214:215] op_sel_hi:[1,0]
	v_pk_mul_f32 v[30:31], v[30:31], v[214:215] op_sel_hi:[1,0]
	v_pk_mul_f32 v[24:25], v[24:25], v[214:215] op_sel_hi:[1,0]
	v_pk_mul_f32 v[26:27], v[26:27], v[214:215] op_sel_hi:[1,0]
	v_pk_mul_f32 v[20:21], v[20:21], v[214:215] op_sel_hi:[1,0]
	v_pk_mul_f32 v[22:23], v[22:23], v[214:215] op_sel_hi:[1,0]
	v_pk_mul_f32 v[16:17], v[16:17], v[214:215] op_sel_hi:[1,0]
	v_pk_mul_f32 v[18:19], v[18:19], v[214:215] op_sel_hi:[1,0]
	v_pk_mul_f32 v[146:147], v[28:29], v[28:29]
	v_pk_mul_f32 v[148:149], v[30:31], v[30:31]
	v_pk_fma_f32 v[146:147], v[24:25], v[24:25], v[146:147]
	v_pk_fma_f32 v[148:149], v[26:27], v[26:27], v[148:149]
	v_pk_fma_f32 v[146:147], v[20:21], v[20:21], v[146:147]
	v_pk_fma_f32 v[148:149], v[22:23], v[22:23], v[148:149]
	v_pk_fma_f32 v[146:147], v[16:17], v[16:17], v[146:147]
	v_pk_fma_f32 v[148:149], v[18:19], v[18:19], v[148:149]
	s_nop 0
	v_pk_add_f32 v[146:147], v[146:147], v[148:149]
	s_nop 0
	v_add_f32_e32 v224, v146, v147
	v_pk_mul_f32 v[12:13], v[12:13], v[216:217] op_sel_hi:[1,0]
	v_pk_mul_f32 v[14:15], v[14:15], v[216:217] op_sel_hi:[1,0]
	v_pk_mul_f32 v[8:9], v[8:9], v[216:217] op_sel_hi:[1,0]
	v_pk_mul_f32 v[10:11], v[10:11], v[216:217] op_sel_hi:[1,0]
	v_pk_mul_f32 v[4:5], v[4:5], v[216:217] op_sel_hi:[1,0]
	v_pk_mul_f32 v[6:7], v[6:7], v[216:217] op_sel_hi:[1,0]
	v_pk_mul_f32 v[0:1], v[0:1], v[216:217] op_sel_hi:[1,0]
	v_pk_mul_f32 v[2:3], v[2:3], v[216:217] op_sel_hi:[1,0]
	v_pk_mul_f32 v[146:147], v[12:13], v[12:13]
	v_pk_mul_f32 v[148:149], v[14:15], v[14:15]
	v_pk_fma_f32 v[146:147], v[8:9], v[8:9], v[146:147]
	v_pk_fma_f32 v[148:149], v[10:11], v[10:11], v[148:149]
	v_pk_fma_f32 v[146:147], v[4:5], v[4:5], v[146:147]
	v_pk_fma_f32 v[148:149], v[6:7], v[6:7], v[148:149]
	v_pk_fma_f32 v[146:147], v[0:1], v[0:1], v[146:147]
	v_pk_fma_f32 v[148:149], v[2:3], v[2:3], v[148:149]
	s_nop 0
	v_pk_add_f32 v[146:147], v[146:147], v[148:149]
	s_nop 0
	v_add_f32_e32 v225, v146, v147
	ds_bpermute_b32 v226, v234, v218
	ds_bpermute_b32 v227, v234, v219
	ds_bpermute_b32 v228, v234, v220
	ds_bpermute_b32 v229, v234, v221
	ds_bpermute_b32 v230, v234, v222
	ds_bpermute_b32 v231, v234, v223
	ds_bpermute_b32 v232, v234, v224
	ds_bpermute_b32 v233, v234, v225
	s_waitcnt lgkmcnt(7)
	v_add_f32_e32 v218, v218, v226
	s_waitcnt lgkmcnt(6)
	v_add_f32_e32 v219, v219, v227
	s_waitcnt lgkmcnt(5)
	v_add_f32_e32 v220, v220, v228
	s_waitcnt lgkmcnt(4)
	v_add_f32_e32 v221, v221, v229
	s_waitcnt lgkmcnt(3)
	v_add_f32_e32 v222, v222, v230
	s_waitcnt lgkmcnt(2)
	v_add_f32_e32 v223, v223, v231
	s_waitcnt lgkmcnt(1)
	v_add_f32_e32 v224, v224, v232
	s_waitcnt lgkmcnt(0)
	v_add_f32_e32 v225, v225, v233
	ds_bpermute_b32 v226, v235, v218
	ds_bpermute_b32 v227, v235, v219
	ds_bpermute_b32 v228, v235, v220
	ds_bpermute_b32 v229, v235, v221
	ds_bpermute_b32 v230, v235, v222
	ds_bpermute_b32 v231, v235, v223
	ds_bpermute_b32 v232, v235, v224
	ds_bpermute_b32 v233, v235, v225
	s_waitcnt lgkmcnt(7)
	v_add_f32_e32 v218, v218, v226
	s_waitcnt lgkmcnt(6)
	v_add_f32_e32 v219, v219, v227
	s_waitcnt lgkmcnt(5)
	v_add_f32_e32 v220, v220, v228
	s_waitcnt lgkmcnt(4)
	v_add_f32_e32 v221, v221, v229
	s_waitcnt lgkmcnt(3)
	v_add_f32_e32 v222, v222, v230
	s_waitcnt lgkmcnt(2)
	v_add_f32_e32 v223, v223, v231
	s_waitcnt lgkmcnt(1)
	v_add_f32_e32 v224, v224, v232
	s_waitcnt lgkmcnt(0)
	v_add_f32_e32 v225, v225, v233
	v_fmamk_f32 v218, v218, 0x3c800000, v181
	v_fmamk_f32 v219, v219, 0x3c800000, v181
	v_fmamk_f32 v220, v220, 0x3c800000, v181
	v_fmamk_f32 v221, v221, 0x3c800000, v181
	v_fmamk_f32 v222, v222, 0x3c800000, v181
	v_fmamk_f32 v223, v223, 0x3c800000, v181
	v_fmamk_f32 v224, v224, 0x3c800000, v181
	v_fmamk_f32 v225, v225, 0x3c800000, v181
	v_rsq_f32_e32 v218, v218
	v_rsq_f32_e32 v219, v219
	v_rsq_f32_e32 v220, v220
	v_rsq_f32_e32 v221, v221
	v_rsq_f32_e32 v222, v222
	v_rsq_f32_e32 v223, v223
	v_rsq_f32_e32 v224, v224
	v_rsq_f32_e32 v225, v225
	v_mul_f32_e32 v202, v144, v218
	v_mul_f32_e32 v204, v144, v219
	v_mul_f32_e32 v206, v144, v220
	v_mul_f32_e32 v208, v144, v221
	v_mul_f32_e32 v210, v144, v222
	v_mul_f32_e32 v212, v144, v223
	v_mul_f32_e32 v214, v144, v224
	v_mul_f32_e32 v216, v144, v225
	s_waitcnt vmcnt(0)
	v_pk_mul_f32 v[124:125], v[124:125], v[202:203] op_sel_hi:[1,0]
	v_pk_mul_f32 v[126:127], v[126:127], v[202:203] op_sel_hi:[1,0]
	v_pk_mul_f32 v[120:121], v[120:121], v[202:203] op_sel_hi:[1,0]
	v_pk_mul_f32 v[122:123], v[122:123], v[202:203] op_sel_hi:[1,0]
	v_pk_mul_f32 v[116:117], v[116:117], v[202:203] op_sel_hi:[1,0]
	v_pk_mul_f32 v[118:119], v[118:119], v[202:203] op_sel_hi:[1,0]
	v_pk_mul_f32 v[112:113], v[112:113], v[202:203] op_sel_hi:[1,0]
	v_pk_mul_f32 v[114:115], v[114:115], v[202:203] op_sel_hi:[1,0]
	v_pk_mul_f32 v[124:125], v[186:187], v[124:125]
	v_pk_mul_f32 v[126:127], v[188:189], v[126:127]
	v_pk_mul_f32 v[120:121], v[190:191], v[120:121]
	v_pk_mul_f32 v[122:123], v[192:193], v[122:123]
	v_pk_mul_f32 v[116:117], v[194:195], v[116:117]
	v_pk_mul_f32 v[118:119], v[196:197], v[118:119]
	v_pk_mul_f32 v[112:113], v[198:199], v[112:113]
	v_pk_mul_f32 v[114:115], v[200:201], v[114:115]
	v_cvt_pk_bf16_f32 v124, v124, v125
	v_cvt_pk_bf16_f32 v125, v126, v127
	v_cvt_pk_bf16_f32 v126, v120, v121
	v_cvt_pk_bf16_f32 v127, v122, v123
	v_cvt_pk_bf16_f32 v116, v116, v117
	v_cvt_pk_bf16_f32 v117, v118, v119
	v_cvt_pk_bf16_f32 v118, v112, v113
	v_cvt_pk_bf16_f32 v119, v114, v115
	global_store_dwordx4 v[238:239], v[124:127], off
	global_store_dwordx4 v[238:239], v[116:119], off offset:16
	v_pk_mul_f32 v[108:109], v[108:109], v[204:205] op_sel_hi:[1,0]
	v_pk_mul_f32 v[110:111], v[110:111], v[204:205] op_sel_hi:[1,0]
	v_pk_mul_f32 v[104:105], v[104:105], v[204:205] op_sel_hi:[1,0]
	v_pk_mul_f32 v[106:107], v[106:107], v[204:205] op_sel_hi:[1,0]
	v_pk_mul_f32 v[100:101], v[100:101], v[204:205] op_sel_hi:[1,0]
	v_pk_mul_f32 v[102:103], v[102:103], v[204:205] op_sel_hi:[1,0]
	v_pk_mul_f32 v[96:97], v[96:97], v[204:205] op_sel_hi:[1,0]
	v_pk_mul_f32 v[98:99], v[98:99], v[204:205] op_sel_hi:[1,0]
	v_pk_mul_f32 v[108:109], v[186:187], v[108:109]
	v_pk_mul_f32 v[110:111], v[188:189], v[110:111]
	v_pk_mul_f32 v[104:105], v[190:191], v[104:105]
	v_pk_mul_f32 v[106:107], v[192:193], v[106:107]
	v_pk_mul_f32 v[100:101], v[194:195], v[100:101]
	v_pk_mul_f32 v[102:103], v[196:197], v[102:103]
	v_pk_mul_f32 v[96:97], v[198:199], v[96:97]
	v_pk_mul_f32 v[98:99], v[200:201], v[98:99]
	v_cvt_pk_bf16_f32 v108, v108, v109
	v_cvt_pk_bf16_f32 v109, v110, v111
	v_cvt_pk_bf16_f32 v110, v104, v105
	v_cvt_pk_bf16_f32 v111, v106, v107
	v_cvt_pk_bf16_f32 v100, v100, v101
	v_cvt_pk_bf16_f32 v101, v102, v103
	v_cvt_pk_bf16_f32 v102, v96, v97
	v_cvt_pk_bf16_f32 v103, v98, v99
	v_add_co_u32_e32 v142, vcc, 0x4000, v238
	s_nop 1
	v_addc_co_u32_e32 v143, vcc, 0, v239, vcc
	global_store_dwordx4 v[142:143], v[108:111], off
	global_store_dwordx4 v[142:143], v[100:103], off offset:16
	v_pk_mul_f32 v[92:93], v[92:93], v[206:207] op_sel_hi:[1,0]
	v_pk_mul_f32 v[94:95], v[94:95], v[206:207] op_sel_hi:[1,0]
	v_pk_mul_f32 v[88:89], v[88:89], v[206:207] op_sel_hi:[1,0]
	v_pk_mul_f32 v[90:91], v[90:91], v[206:207] op_sel_hi:[1,0]
	v_pk_mul_f32 v[84:85], v[84:85], v[206:207] op_sel_hi:[1,0]
	v_pk_mul_f32 v[86:87], v[86:87], v[206:207] op_sel_hi:[1,0]
	v_pk_mul_f32 v[80:81], v[80:81], v[206:207] op_sel_hi:[1,0]
	v_pk_mul_f32 v[82:83], v[82:83], v[206:207] op_sel_hi:[1,0]
	v_pk_mul_f32 v[92:93], v[186:187], v[92:93]
	v_pk_mul_f32 v[94:95], v[188:189], v[94:95]
	v_pk_mul_f32 v[88:89], v[190:191], v[88:89]
	v_pk_mul_f32 v[90:91], v[192:193], v[90:91]
	v_pk_mul_f32 v[84:85], v[194:195], v[84:85]
	v_pk_mul_f32 v[86:87], v[196:197], v[86:87]
	v_pk_mul_f32 v[80:81], v[198:199], v[80:81]
	v_pk_mul_f32 v[82:83], v[200:201], v[82:83]
	v_cvt_pk_bf16_f32 v92, v92, v93
	v_cvt_pk_bf16_f32 v93, v94, v95
	v_cvt_pk_bf16_f32 v94, v88, v89
	v_cvt_pk_bf16_f32 v95, v90, v91
	v_cvt_pk_bf16_f32 v84, v84, v85
	v_cvt_pk_bf16_f32 v85, v86, v87
	v_cvt_pk_bf16_f32 v86, v80, v81
	v_cvt_pk_bf16_f32 v87, v82, v83
	v_add_co_u32_e32 v142, vcc, 0x8000, v238
	s_nop 1
	v_addc_co_u32_e32 v143, vcc, 0, v239, vcc
	global_store_dwordx4 v[142:143], v[92:95], off
	global_store_dwordx4 v[142:143], v[84:87], off offset:16
	v_pk_mul_f32 v[76:77], v[76:77], v[208:209] op_sel_hi:[1,0]
	v_pk_mul_f32 v[78:79], v[78:79], v[208:209] op_sel_hi:[1,0]
	v_pk_mul_f32 v[72:73], v[72:73], v[208:209] op_sel_hi:[1,0]
	v_pk_mul_f32 v[74:75], v[74:75], v[208:209] op_sel_hi:[1,0]
	v_pk_mul_f32 v[68:69], v[68:69], v[208:209] op_sel_hi:[1,0]
	v_pk_mul_f32 v[70:71], v[70:71], v[208:209] op_sel_hi:[1,0]
	v_pk_mul_f32 v[64:65], v[64:65], v[208:209] op_sel_hi:[1,0]
	v_pk_mul_f32 v[66:67], v[66:67], v[208:209] op_sel_hi:[1,0]
	v_pk_mul_f32 v[76:77], v[186:187], v[76:77]
	v_pk_mul_f32 v[78:79], v[188:189], v[78:79]
	v_pk_mul_f32 v[72:73], v[190:191], v[72:73]
	v_pk_mul_f32 v[74:75], v[192:193], v[74:75]
	v_pk_mul_f32 v[68:69], v[194:195], v[68:69]
	v_pk_mul_f32 v[70:71], v[196:197], v[70:71]
	v_pk_mul_f32 v[64:65], v[198:199], v[64:65]
	v_pk_mul_f32 v[66:67], v[200:201], v[66:67]
	v_cvt_pk_bf16_f32 v76, v76, v77
	v_cvt_pk_bf16_f32 v77, v78, v79
	v_cvt_pk_bf16_f32 v78, v72, v73
	v_cvt_pk_bf16_f32 v79, v74, v75
	v_cvt_pk_bf16_f32 v68, v68, v69
	v_cvt_pk_bf16_f32 v69, v70, v71
	v_cvt_pk_bf16_f32 v70, v64, v65
	v_cvt_pk_bf16_f32 v71, v66, v67
	v_add_co_u32_e32 v142, vcc, 0xc000, v238
	s_nop 1
	v_addc_co_u32_e32 v143, vcc, 0, v239, vcc
	global_store_dwordx4 v[142:143], v[76:79], off
	global_store_dwordx4 v[142:143], v[68:71], off offset:16
	v_pk_mul_f32 v[60:61], v[60:61], v[210:211] op_sel_hi:[1,0]
	v_pk_mul_f32 v[62:63], v[62:63], v[210:211] op_sel_hi:[1,0]
	v_pk_mul_f32 v[56:57], v[56:57], v[210:211] op_sel_hi:[1,0]
	v_pk_mul_f32 v[58:59], v[58:59], v[210:211] op_sel_hi:[1,0]
	v_pk_mul_f32 v[52:53], v[52:53], v[210:211] op_sel_hi:[1,0]
	v_pk_mul_f32 v[54:55], v[54:55], v[210:211] op_sel_hi:[1,0]
	v_pk_mul_f32 v[48:49], v[48:49], v[210:211] op_sel_hi:[1,0]
	v_pk_mul_f32 v[50:51], v[50:51], v[210:211] op_sel_hi:[1,0]
	v_pk_mul_f32 v[60:61], v[186:187], v[60:61]
	v_pk_mul_f32 v[62:63], v[188:189], v[62:63]
	v_pk_mul_f32 v[56:57], v[190:191], v[56:57]
	v_pk_mul_f32 v[58:59], v[192:193], v[58:59]
	v_pk_mul_f32 v[52:53], v[194:195], v[52:53]
	v_pk_mul_f32 v[54:55], v[196:197], v[54:55]
	v_pk_mul_f32 v[48:49], v[198:199], v[48:49]
	v_pk_mul_f32 v[50:51], v[200:201], v[50:51]
	v_cvt_pk_bf16_f32 v60, v60, v61
	v_cvt_pk_bf16_f32 v61, v62, v63
	v_cvt_pk_bf16_f32 v62, v56, v57
	v_cvt_pk_bf16_f32 v63, v58, v59
	v_cvt_pk_bf16_f32 v52, v52, v53
	v_cvt_pk_bf16_f32 v53, v54, v55
	v_cvt_pk_bf16_f32 v54, v48, v49
	v_cvt_pk_bf16_f32 v55, v50, v51
	v_add_co_u32_e32 v142, vcc, 0x20000, v238
	s_nop 1
	v_addc_co_u32_e32 v143, vcc, 0, v239, vcc
	global_store_dwordx4 v[142:143], v[60:63], off
	global_store_dwordx4 v[142:143], v[52:55], off offset:16
	v_pk_mul_f32 v[44:45], v[44:45], v[212:213] op_sel_hi:[1,0]
	v_pk_mul_f32 v[46:47], v[46:47], v[212:213] op_sel_hi:[1,0]
	v_pk_mul_f32 v[40:41], v[40:41], v[212:213] op_sel_hi:[1,0]
	v_pk_mul_f32 v[42:43], v[42:43], v[212:213] op_sel_hi:[1,0]
	v_pk_mul_f32 v[36:37], v[36:37], v[212:213] op_sel_hi:[1,0]
	v_pk_mul_f32 v[38:39], v[38:39], v[212:213] op_sel_hi:[1,0]
	v_pk_mul_f32 v[32:33], v[32:33], v[212:213] op_sel_hi:[1,0]
	v_pk_mul_f32 v[34:35], v[34:35], v[212:213] op_sel_hi:[1,0]
	v_pk_mul_f32 v[44:45], v[186:187], v[44:45]
	v_pk_mul_f32 v[46:47], v[188:189], v[46:47]
	v_pk_mul_f32 v[40:41], v[190:191], v[40:41]
	v_pk_mul_f32 v[42:43], v[192:193], v[42:43]
	v_pk_mul_f32 v[36:37], v[194:195], v[36:37]
	v_pk_mul_f32 v[38:39], v[196:197], v[38:39]
	v_pk_mul_f32 v[32:33], v[198:199], v[32:33]
	v_pk_mul_f32 v[34:35], v[200:201], v[34:35]
	v_cvt_pk_bf16_f32 v44, v44, v45
	v_cvt_pk_bf16_f32 v45, v46, v47
	v_cvt_pk_bf16_f32 v46, v40, v41
	v_cvt_pk_bf16_f32 v47, v42, v43
	v_cvt_pk_bf16_f32 v36, v36, v37
	v_cvt_pk_bf16_f32 v37, v38, v39
	v_cvt_pk_bf16_f32 v38, v32, v33
	v_cvt_pk_bf16_f32 v39, v34, v35
	v_add_co_u32_e32 v142, vcc, 0x24000, v238
	s_nop 1
	v_addc_co_u32_e32 v143, vcc, 0, v239, vcc
	global_store_dwordx4 v[142:143], v[44:47], off
	global_store_dwordx4 v[142:143], v[36:39], off offset:16
	v_pk_mul_f32 v[28:29], v[28:29], v[214:215] op_sel_hi:[1,0]
	v_pk_mul_f32 v[30:31], v[30:31], v[214:215] op_sel_hi:[1,0]
	v_pk_mul_f32 v[24:25], v[24:25], v[214:215] op_sel_hi:[1,0]
	v_pk_mul_f32 v[26:27], v[26:27], v[214:215] op_sel_hi:[1,0]
	v_pk_mul_f32 v[20:21], v[20:21], v[214:215] op_sel_hi:[1,0]
	v_pk_mul_f32 v[22:23], v[22:23], v[214:215] op_sel_hi:[1,0]
	v_pk_mul_f32 v[16:17], v[16:17], v[214:215] op_sel_hi:[1,0]
	v_pk_mul_f32 v[18:19], v[18:19], v[214:215] op_sel_hi:[1,0]
	v_pk_mul_f32 v[28:29], v[186:187], v[28:29]
	v_pk_mul_f32 v[30:31], v[188:189], v[30:31]
	v_pk_mul_f32 v[24:25], v[190:191], v[24:25]
	v_pk_mul_f32 v[26:27], v[192:193], v[26:27]
	v_pk_mul_f32 v[20:21], v[194:195], v[20:21]
	v_pk_mul_f32 v[22:23], v[196:197], v[22:23]
	v_pk_mul_f32 v[16:17], v[198:199], v[16:17]
	v_pk_mul_f32 v[18:19], v[200:201], v[18:19]
	v_cvt_pk_bf16_f32 v28, v28, v29
	v_cvt_pk_bf16_f32 v29, v30, v31
	v_cvt_pk_bf16_f32 v30, v24, v25
	v_cvt_pk_bf16_f32 v31, v26, v27
	v_cvt_pk_bf16_f32 v20, v20, v21
	v_cvt_pk_bf16_f32 v21, v22, v23
	v_cvt_pk_bf16_f32 v22, v16, v17
	v_cvt_pk_bf16_f32 v23, v18, v19
	v_add_co_u32_e32 v142, vcc, 0x28000, v238
	s_nop 1
	v_addc_co_u32_e32 v143, vcc, 0, v239, vcc
	global_store_dwordx4 v[142:143], v[28:31], off
	global_store_dwordx4 v[142:143], v[20:23], off offset:16
	v_pk_mul_f32 v[12:13], v[12:13], v[216:217] op_sel_hi:[1,0]
	v_pk_mul_f32 v[14:15], v[14:15], v[216:217] op_sel_hi:[1,0]
	v_pk_mul_f32 v[8:9], v[8:9], v[216:217] op_sel_hi:[1,0]
	v_pk_mul_f32 v[10:11], v[10:11], v[216:217] op_sel_hi:[1,0]
	v_pk_mul_f32 v[4:5], v[4:5], v[216:217] op_sel_hi:[1,0]
	v_pk_mul_f32 v[6:7], v[6:7], v[216:217] op_sel_hi:[1,0]
	v_pk_mul_f32 v[0:1], v[0:1], v[216:217] op_sel_hi:[1,0]
	v_pk_mul_f32 v[2:3], v[2:3], v[216:217] op_sel_hi:[1,0]
	v_pk_mul_f32 v[12:13], v[186:187], v[12:13]
	v_pk_mul_f32 v[14:15], v[188:189], v[14:15]
	v_pk_mul_f32 v[8:9], v[190:191], v[8:9]
	v_pk_mul_f32 v[10:11], v[192:193], v[10:11]
	v_pk_mul_f32 v[4:5], v[194:195], v[4:5]
	v_pk_mul_f32 v[6:7], v[196:197], v[6:7]
	v_pk_mul_f32 v[0:1], v[198:199], v[0:1]
	v_pk_mul_f32 v[2:3], v[200:201], v[2:3]
	v_cvt_pk_bf16_f32 v12, v12, v13
	v_cvt_pk_bf16_f32 v13, v14, v15
	v_cvt_pk_bf16_f32 v14, v8, v9
	v_cvt_pk_bf16_f32 v15, v10, v11
	v_cvt_pk_bf16_f32 v4, v4, v5
	v_cvt_pk_bf16_f32 v5, v6, v7
	v_cvt_pk_bf16_f32 v6, v0, v1
	v_cvt_pk_bf16_f32 v7, v2, v3
	v_add_co_u32_e32 v142, vcc, 0x2c000, v238
	s_nop 1
	v_addc_co_u32_e32 v143, vcc, 0, v239, vcc
	global_store_dwordx4 v[142:143], v[12:15], off
	global_store_dwordx4 v[142:143], v[4:7], off offset:16
	s_andn2_b64 vcc, exec, s[4:5]
	s_mov_b64 s[4:5], -1
	s_cbranch_vccnz .LBB0_124
